# norm_rows loops (phases 1, 9): reload path drains itself, tail prefetch blocks drain out of line, common path uses exact counted vmcnt waits (prefetch no longer defeated)
# speedup vs baseline: 1.0273x; 1.0016x over previous
.LBB0_233:
	s_or_b64 exec, exec, s[24:25]
	s_waitcnt vmcnt(24)
	v_mov_b32_e32 v124, v57
	v_mov_b32_e32 v125, v61
	v_mov_b32_e32 v122, v56
	v_mov_b32_e32 v123, v60
	v_pk_mul_f32 v[124:125], v[124:125], v[124:125]
	v_mov_b32_e32 v134, v49
	v_pk_fma_f32 v[122:123], v[122:123], v[122:123], v[124:125]
	v_mov_b32_e32 v124, v58
	v_mov_b32_e32 v125, v62
	v_pk_fma_f32 v[122:123], v[124:125], v[124:125], v[122:123]
	v_mov_b32_e32 v124, v59
	v_mov_b32_e32 v125, v63
	v_mov_b32_e32 v135, v53
	v_pk_fma_f32 v[122:123], v[124:125], v[124:125], v[122:123]
	v_mov_b32_e32 v124, v48
	v_mov_b32_e32 v125, v52
	v_pk_mul_f32 v[134:135], v[134:135], v[134:135]
	v_add_f32_e32 v119, v122, v123
	v_pk_fma_f32 v[124:125], v[124:125], v[124:125], v[134:135]
	v_mov_b32_e32 v134, v50
	v_mov_b32_e32 v135, v54
	v_pk_fma_f32 v[124:125], v[134:135], v[134:135], v[124:125]
	v_mov_b32_e32 v134, v51
	v_mov_b32_e32 v135, v55
	v_pk_fma_f32 v[124:125], v[134:135], v[134:135], v[124:125]
	s_nop 0
	v_add_f32_e32 v119, v125, v119
	v_add_f32_e32 v119, v124, v119
	ds_bpermute_b32 v122, v105, v119
	s_waitcnt lgkmcnt(0)
	v_add_f32_e32 v119, v119, v122
	ds_bpermute_b32 v122, v126, v119
	s_waitcnt lgkmcnt(0)
	v_add_f32_e32 v119, v119, v122
	ds_bpermute_b32 v122, v127, v119
	s_waitcnt lgkmcnt(0)
	v_add_f32_e32 v119, v119, v122
	ds_bpermute_b32 v122, v128, v119
	s_waitcnt lgkmcnt(0)
	v_add_f32_e32 v119, v119, v122
	ds_bpermute_b32 v122, v129, v119
	s_waitcnt lgkmcnt(0)
	v_add_f32_e32 v119, v119, v122
	ds_bpermute_b32 v122, v130, v119
	s_waitcnt lgkmcnt(0)
	v_add_f32_e32 v119, v119, v122
	v_fmamk_f32 v119, v119, 0x3a800000, v131
	v_mul_f32_e32 v122, 0x4b800000, v119
	v_cmp_gt_f32_e32 vcc, s42, v119
	s_nop 1
	v_cndmask_b32_e32 v119, v119, v122, vcc
	v_rsq_f32_e32 v119, v119
	v_lshl_add_u64 v[122:123], v[114:115], 0, v[112:113]
	v_mul_f32_e32 v124, 0x45800000, v119
	v_cndmask_b32_e32 v124, v119, v124, vcc
	v_pk_mul_f32 v[134:135], v[60:61], v[124:125] op_sel_hi:[1,0]
	v_pk_mul_f32 v[136:137], v[62:63], v[124:125] op_sel_hi:[1,0]
	v_pk_fma_f32 v[134:135], v[80:81], v[134:135], v[64:65]
	v_pk_fma_f32 v[136:137], v[82:83], v[136:137], v[66:67]
	v_add_co_u32_e32 v122, vcc, s43, v122
	v_cvt_pk_bf16_f32 v134, v134, v135
	v_cvt_pk_bf16_f32 v135, v136, v137
	v_addc_co_u32_e32 v123, vcc, 0, v123, vcc
	global_store_dwordx2 v[122:123], v[134:135], off
	v_pk_mul_f32 v[134:135], v[56:57], v[124:125] op_sel_hi:[1,0]
	v_pk_mul_f32 v[136:137], v[58:59], v[124:125] op_sel_hi:[1,0]
	v_pk_fma_f32 v[134:135], v[84:85], v[134:135], v[68:69]
	v_pk_fma_f32 v[136:137], v[86:87], v[136:137], v[70:71]
	v_cvt_pk_bf16_f32 v134, v134, v135
	v_cvt_pk_bf16_f32 v135, v136, v137
	global_store_dwordx2 v[122:123], v[134:135], off offset:512
	v_pk_mul_f32 v[134:135], v[52:53], v[124:125] op_sel_hi:[1,0]
	v_pk_mul_f32 v[136:137], v[54:55], v[124:125] op_sel_hi:[1,0]
	v_pk_fma_f32 v[134:135], v[88:89], v[134:135], v[72:73]
	v_pk_fma_f32 v[136:137], v[90:91], v[136:137], v[74:75]
	v_cvt_pk_bf16_f32 v134, v134, v135
	v_cvt_pk_bf16_f32 v135, v136, v137
	global_store_dwordx2 v[122:123], v[134:135], off offset:1024
	v_pk_mul_f32 v[134:135], v[48:49], v[124:125] op_sel_hi:[1,0]
	v_pk_mul_f32 v[124:125], v[50:51], v[124:125] op_sel_hi:[1,0]
	v_pk_fma_f32 v[134:135], v[92:93], v[134:135], v[76:77]
	v_pk_fma_f32 v[124:125], v[94:95], v[124:125], v[78:79]
	v_cvt_pk_bf16_f32 v134, v134, v135
	v_cvt_pk_bf16_f32 v135, v124, v125
	global_store_dwordx2 v[122:123], v[134:135], off offset:1536

.LBB0_237:
	s_or_b64 exec, exec, s[0:1]
	v_add_u32_e32 v119, -6, v118
	v_ashrrev_i32_e32 v119, 12, v119
	v_cmp_ne_u32_e64 s[0:1], v119, v132
	s_and_saveexec_b64 s[24:25], s[0:1]
	s_cbranch_execz .LBB0_239
	v_mul_hi_i32_i24_e32 v65, 0x6000, v119
	v_mul_i32_i24_e32 v64, 0x6000, v119
	v_lshl_add_u64 v[64:65], s[88:89], 0, v[64:65]
	v_lshl_add_u64 v[66:67], v[64:65], 0, s[14:15]
	v_lshl_add_u64 v[68:69], v[66:67], 0, v[96:97]
	global_load_dwordx4 v[80:83], v[68:69], off nt
	v_lshlrev_b32_e32 v68, 2, v102
	v_mov_b32_e32 v69, v97
	v_lshl_add_u64 v[68:69], v[66:67], 0, v[68:69]
	global_load_dwordx4 v[84:87], v[68:69], off nt
	v_lshlrev_b32_e32 v68, 2, v98
	v_mov_b32_e32 v69, v97
	v_lshl_add_u64 v[68:69], v[66:67], 0, v[68:69]
	global_load_dwordx4 v[88:91], v[68:69], off nt
	v_lshlrev_b32_e32 v68, 2, v104
	v_mov_b32_e32 v69, v97
	v_lshl_add_u64 v[66:67], v[66:67], 0, v[68:69]
	global_load_dwordx4 v[92:95], v[66:67], off nt
	global_load_dwordx4 v[122:125], v[106:107], off nt
	global_load_dwordx4 v[136:139], v[106:107], off offset:1024 nt
	v_lshl_add_u64 v[76:77], v[64:65], 0, v[96:97]
	global_load_dwordx4 v[140:143], v[106:107], off offset:2048 nt
	global_load_dwordx4 v[64:67], v[76:77], off nt
	global_load_dwordx4 v[144:147], v[106:107], off offset:3072 nt
	global_load_dwordx4 v[68:71], v[76:77], off offset:1024 nt
	global_load_dwordx4 v[72:75], v[76:77], off offset:2048 nt
	s_nop 0
	global_load_dwordx4 v[76:79], v[76:77], off offset:3072 nt
	v_mov_b32_e32 v132, v119
	s_waitcnt vmcnt(11)
	v_pk_add_f32 v[82:83], v[82:83], 1.0 op_sel_hi:[1,0]
	v_pk_add_f32 v[80:81], v[80:81], 1.0 op_sel_hi:[1,0]
	s_waitcnt vmcnt(10)
	v_pk_add_f32 v[86:87], v[86:87], 1.0 op_sel_hi:[1,0]
	v_pk_add_f32 v[84:85], v[84:85], 1.0 op_sel_hi:[1,0]
	s_waitcnt vmcnt(9)
	v_pk_add_f32 v[90:91], v[90:91], 1.0 op_sel_hi:[1,0]
	v_pk_add_f32 v[88:89], v[88:89], 1.0 op_sel_hi:[1,0]
	s_waitcnt vmcnt(8)
	v_pk_add_f32 v[94:95], v[94:95], 1.0 op_sel_hi:[1,0]
	v_pk_add_f32 v[92:93], v[92:93], 1.0 op_sel_hi:[1,0]
	s_waitcnt vmcnt(7)
	v_pk_mul_f32 v[82:83], v[124:125], v[82:83]
	v_pk_mul_f32 v[80:81], v[122:123], v[80:81]
	s_waitcnt vmcnt(6)
	v_pk_mul_f32 v[86:87], v[138:139], v[86:87]
	v_pk_mul_f32 v[84:85], v[136:137], v[84:85]
	s_waitcnt vmcnt(5)
	v_pk_mul_f32 v[90:91], v[142:143], v[90:91]
	v_pk_mul_f32 v[88:89], v[140:141], v[88:89]
	s_waitcnt vmcnt(3)
	v_pk_mul_f32 v[94:95], v[146:147], v[94:95]
	v_pk_mul_f32 v[92:93], v[144:145], v[92:93]
	s_waitcnt vmcnt(0)
.LBB0_239:
	s_or_b64 exec, exec, s[24:25]
	s_waitcnt vmcnt(12)
	v_mov_b32_e32 v124, v5
	v_mov_b32_e32 v125, v1
	v_mov_b32_e32 v122, v4
	v_mov_b32_e32 v123, v0
	v_pk_mul_f32 v[124:125], v[124:125], v[124:125]
	v_mov_b32_e32 v136, v13
	v_pk_fma_f32 v[122:123], v[122:123], v[122:123], v[124:125]
	v_mov_b32_e32 v124, v6
	v_mov_b32_e32 v125, v2
	v_pk_fma_f32 v[122:123], v[124:125], v[124:125], v[122:123]
	v_mov_b32_e32 v124, v7
	v_mov_b32_e32 v125, v3
	v_mov_b32_e32 v137, v9
	v_pk_fma_f32 v[122:123], v[124:125], v[124:125], v[122:123]
	v_mov_b32_e32 v124, v12
	v_mov_b32_e32 v125, v8
	v_pk_mul_f32 v[136:137], v[136:137], v[136:137]
	v_add_f32_e32 v119, v122, v123
	v_pk_fma_f32 v[124:125], v[124:125], v[124:125], v[136:137]
	v_mov_b32_e32 v136, v14
	v_mov_b32_e32 v137, v10
	v_pk_fma_f32 v[124:125], v[136:137], v[136:137], v[124:125]
	v_mov_b32_e32 v136, v15
	v_mov_b32_e32 v137, v11
	v_pk_fma_f32 v[124:125], v[136:137], v[136:137], v[124:125]
	v_add_u32_e32 v133, -2, v118
	v_add_f32_e32 v119, v125, v119
	v_add_f32_e32 v119, v124, v119
	ds_bpermute_b32 v122, v105, v119
	s_waitcnt lgkmcnt(0)
	v_add_f32_e32 v119, v119, v122
	ds_bpermute_b32 v122, v126, v119
	s_waitcnt lgkmcnt(0)
	v_add_f32_e32 v119, v119, v122
	ds_bpermute_b32 v122, v127, v119
	s_waitcnt lgkmcnt(0)
	v_add_f32_e32 v119, v119, v122
	ds_bpermute_b32 v122, v128, v119
	s_waitcnt lgkmcnt(0)
	v_add_f32_e32 v119, v119, v122
	ds_bpermute_b32 v122, v129, v119
	s_waitcnt lgkmcnt(0)
	v_add_f32_e32 v119, v119, v122
	ds_bpermute_b32 v122, v130, v119
	s_waitcnt lgkmcnt(0)
	v_add_f32_e32 v119, v119, v122
	v_fmamk_f32 v119, v119, 0x3a800000, v131
	v_mul_f32_e32 v122, 0x4b800000, v119
	v_cmp_gt_f32_e64 s[0:1], s42, v119
	s_nop 1
	v_cndmask_b32_e64 v119, v119, v122, s[0:1]
	v_rsq_f32_e32 v119, v119
	v_lshl_add_u64 v[122:123], v[120:121], 0, v[112:113]
	v_mul_f32_e32 v124, 0x45800000, v119
	v_cndmask_b32_e64 v124, v119, v124, s[0:1]
	v_pk_mul_f32 v[136:137], v[0:1], v[124:125] op_sel_hi:[1,0]
	v_pk_mul_f32 v[138:139], v[2:3], v[124:125] op_sel_hi:[1,0]
	v_pk_fma_f32 v[136:137], v[80:81], v[136:137], v[64:65]
	v_pk_fma_f32 v[138:139], v[82:83], v[138:139], v[66:67]
	v_add_co_u32_e64 v122, s[0:1], s43, v122
	v_cvt_pk_bf16_f32 v136, v136, v137
	v_cvt_pk_bf16_f32 v137, v138, v139
	v_addc_co_u32_e64 v123, s[0:1], 0, v123, s[0:1]
	global_store_dwordx2 v[122:123], v[136:137], off
	v_pk_mul_f32 v[136:137], v[4:5], v[124:125] op_sel_hi:[1,0]
	v_pk_mul_f32 v[138:139], v[6:7], v[124:125] op_sel_hi:[1,0]
	v_pk_fma_f32 v[136:137], v[84:85], v[136:137], v[68:69]
	v_pk_fma_f32 v[138:139], v[86:87], v[138:139], v[70:71]
	v_cvt_pk_bf16_f32 v136, v136, v137
	v_cvt_pk_bf16_f32 v137, v138, v139
	global_store_dwordx2 v[122:123], v[136:137], off offset:512
	v_pk_mul_f32 v[136:137], v[8:9], v[124:125] op_sel_hi:[1,0]
	v_pk_mul_f32 v[138:139], v[10:11], v[124:125] op_sel_hi:[1,0]
	v_pk_fma_f32 v[136:137], v[88:89], v[136:137], v[72:73]
	v_pk_fma_f32 v[138:139], v[90:91], v[138:139], v[74:75]
	v_cvt_pk_bf16_f32 v136, v136, v137
	v_cvt_pk_bf16_f32 v137, v138, v139
	global_store_dwordx2 v[122:123], v[136:137], off offset:1024
	v_pk_mul_f32 v[136:137], v[12:13], v[124:125] op_sel_hi:[1,0]
	v_pk_mul_f32 v[124:125], v[14:15], v[124:125] op_sel_hi:[1,0]
	v_pk_fma_f32 v[136:137], v[92:93], v[136:137], v[76:77]
	v_pk_fma_f32 v[124:125], v[94:95], v[124:125], v[78:79]
	v_cvt_pk_bf16_f32 v136, v136, v137
	v_cvt_pk_bf16_f32 v137, v124, v125
	global_store_dwordx2 v[122:123], v[136:137], off offset:1536
	v_add_u32_e32 v122, -5, v118
	v_cmp_lt_i32_e64 s[0:1], v122, v103
	s_and_saveexec_b64 s[24:25], s[0:1]
	s_cbranch_execz .LBB0_245
	v_cmp_lt_i32_e64 s[0:1], v133, v103
	s_and_saveexec_b64 s[26:27], s[0:1]
	s_cbranch_execz .Lnr1_t2
	global_load_dwordx4 v[0:3], v[116:117], off offset:-2048 nt
	global_load_dwordx4 v[4:7], v[116:117], off offset:-1024 nt
	global_load_dwordx4 v[8:11], v[116:117], off nt
	global_load_dwordx4 v[12:15], v[116:117], off offset:1024 nt
.LBB0_242:
	s_or_b64 exec, exec, s[26:27]
	v_ashrrev_i32_e32 v119, 12, v122
	v_cmp_ne_u32_e64 s[0:1], v119, v132
	s_and_saveexec_b64 s[26:27], s[0:1]
	s_cbranch_execz .LBB0_244
	v_mul_hi_i32_i24_e32 v65, 0x6000, v119
	v_mul_i32_i24_e32 v64, 0x6000, v119
	v_lshl_add_u64 v[64:65], s[88:89], 0, v[64:65]
	v_lshl_add_u64 v[66:67], v[64:65], 0, s[14:15]
	v_lshl_add_u64 v[68:69], v[66:67], 0, v[96:97]
	global_load_dwordx4 v[80:83], v[68:69], off nt
	v_lshlrev_b32_e32 v68, 2, v102
	v_mov_b32_e32 v69, v97
	v_lshl_add_u64 v[68:69], v[66:67], 0, v[68:69]
	global_load_dwordx4 v[84:87], v[68:69], off nt
	v_lshlrev_b32_e32 v68, 2, v98
	v_mov_b32_e32 v69, v97
	v_lshl_add_u64 v[68:69], v[66:67], 0, v[68:69]
	global_load_dwordx4 v[88:91], v[68:69], off nt
	v_lshlrev_b32_e32 v68, 2, v104
	v_mov_b32_e32 v69, v97
	v_lshl_add_u64 v[66:67], v[66:67], 0, v[68:69]
	global_load_dwordx4 v[92:95], v[66:67], off nt
	global_load_dwordx4 v[136:139], v[106:107], off nt
	global_load_dwordx4 v[140:143], v[106:107], off offset:1024 nt
	v_lshl_add_u64 v[76:77], v[64:65], 0, v[96:97]
	global_load_dwordx4 v[144:147], v[106:107], off offset:2048 nt
	global_load_dwordx4 v[64:67], v[76:77], off nt
	global_load_dwordx4 v[148:151], v[106:107], off offset:3072 nt
	global_load_dwordx4 v[68:71], v[76:77], off offset:1024 nt
	global_load_dwordx4 v[72:75], v[76:77], off offset:2048 nt
	s_nop 0
	global_load_dwordx4 v[76:79], v[76:77], off offset:3072 nt
	v_mov_b32_e32 v132, v119
	s_waitcnt vmcnt(11)
	v_pk_add_f32 v[82:83], v[82:83], 1.0 op_sel_hi:[1,0]
	v_pk_add_f32 v[80:81], v[80:81], 1.0 op_sel_hi:[1,0]
	s_waitcnt vmcnt(10)
	v_pk_add_f32 v[86:87], v[86:87], 1.0 op_sel_hi:[1,0]
	v_pk_add_f32 v[84:85], v[84:85], 1.0 op_sel_hi:[1,0]
	s_waitcnt vmcnt(9)
	v_pk_add_f32 v[90:91], v[90:91], 1.0 op_sel_hi:[1,0]
	v_pk_add_f32 v[88:89], v[88:89], 1.0 op_sel_hi:[1,0]
	s_waitcnt vmcnt(8)
	v_pk_add_f32 v[94:95], v[94:95], 1.0 op_sel_hi:[1,0]
	v_pk_add_f32 v[92:93], v[92:93], 1.0 op_sel_hi:[1,0]
	s_waitcnt vmcnt(7)
	v_pk_mul_f32 v[82:83], v[138:139], v[82:83]
	v_pk_mul_f32 v[80:81], v[136:137], v[80:81]
	s_waitcnt vmcnt(6)
	v_pk_mul_f32 v[86:87], v[142:143], v[86:87]
	v_pk_mul_f32 v[84:85], v[140:141], v[84:85]
	s_waitcnt vmcnt(5)
	v_pk_mul_f32 v[90:91], v[146:147], v[90:91]
	v_pk_mul_f32 v[88:89], v[144:145], v[88:89]
	s_waitcnt vmcnt(3)
	v_pk_mul_f32 v[94:95], v[150:151], v[94:95]
	v_pk_mul_f32 v[92:93], v[148:149], v[92:93]
	s_waitcnt vmcnt(0)
.LBB0_244:
	s_or_b64 exec, exec, s[26:27]
	s_waitcnt vmcnt(16)
	v_mov_b32_e32 v136, v21
	v_mov_b32_e32 v137, v17
	v_mov_b32_e32 v124, v20
	v_mov_b32_e32 v125, v16
	v_pk_mul_f32 v[136:137], v[136:137], v[136:137]
	v_mov_b32_e32 v138, v29
	v_pk_fma_f32 v[124:125], v[124:125], v[124:125], v[136:137]
	v_mov_b32_e32 v136, v22
	v_mov_b32_e32 v137, v18
	v_pk_fma_f32 v[124:125], v[136:137], v[136:137], v[124:125]
	v_mov_b32_e32 v136, v23
	v_mov_b32_e32 v137, v19
	v_mov_b32_e32 v139, v25
	v_pk_fma_f32 v[124:125], v[136:137], v[136:137], v[124:125]
	v_mov_b32_e32 v136, v28
	v_mov_b32_e32 v137, v24
	v_pk_mul_f32 v[138:139], v[138:139], v[138:139]
	v_add_f32_e32 v119, v124, v125
	v_pk_fma_f32 v[136:137], v[136:137], v[136:137], v[138:139]
	v_mov_b32_e32 v138, v30
	v_mov_b32_e32 v139, v26
	v_pk_fma_f32 v[136:137], v[138:139], v[138:139], v[136:137]
	v_mov_b32_e32 v138, v31
	v_mov_b32_e32 v139, v27
	v_pk_fma_f32 v[136:137], v[138:139], v[138:139], v[136:137]
	s_nop 0
	v_add_f32_e32 v119, v137, v119
	v_add_f32_e32 v119, v136, v119
	ds_bpermute_b32 v123, v105, v119
	s_waitcnt lgkmcnt(0)
	v_add_f32_e32 v119, v119, v123
	ds_bpermute_b32 v123, v126, v119
	s_waitcnt lgkmcnt(0)
	v_add_f32_e32 v119, v119, v123
	ds_bpermute_b32 v123, v127, v119
	s_waitcnt lgkmcnt(0)
	v_add_f32_e32 v119, v119, v123
	ds_bpermute_b32 v123, v128, v119
	s_waitcnt lgkmcnt(0)
	v_add_f32_e32 v119, v119, v123
	ds_bpermute_b32 v123, v129, v119
	s_waitcnt lgkmcnt(0)
	v_add_f32_e32 v119, v119, v123
	ds_bpermute_b32 v123, v130, v119
	s_waitcnt lgkmcnt(0)
	v_add_f32_e32 v119, v119, v123
	v_fmamk_f32 v119, v119, 0x3a800000, v131
	v_mul_f32_e32 v123, 0x4b800000, v119
	v_cmp_gt_f32_e64 s[0:1], s42, v119
	s_nop 1
	v_cndmask_b32_e64 v119, v119, v123, s[0:1]
	v_rsq_f32_e32 v119, v119
	v_ashrrev_i32_e32 v123, 31, v122
	v_lshlrev_b64 v[122:123], 11, v[122:123]
	v_lshl_add_u64 v[122:123], v[100:101], 0, v[122:123]
	v_mul_f32_e32 v124, 0x45800000, v119
	v_cndmask_b32_e64 v124, v119, v124, s[0:1]
	v_pk_mul_f32 v[136:137], v[16:17], v[124:125] op_sel_hi:[1,0]
	v_pk_mul_f32 v[138:139], v[18:19], v[124:125] op_sel_hi:[1,0]
	v_pk_fma_f32 v[136:137], v[80:81], v[136:137], v[64:65]
	v_pk_fma_f32 v[138:139], v[82:83], v[138:139], v[66:67]
	v_cvt_pk_bf16_f32 v136, v136, v137
	v_cvt_pk_bf16_f32 v137, v138, v139
	v_pk_mul_f32 v[140:141], v[20:21], v[124:125] op_sel_hi:[1,0]
	global_store_dwordx2 v[122:123], v[136:137], off
	v_pk_mul_f32 v[136:137], v[22:23], v[124:125] op_sel_hi:[1,0]
	v_pk_fma_f32 v[138:139], v[84:85], v[140:141], v[68:69]
	v_pk_fma_f32 v[136:137], v[86:87], v[136:137], v[70:71]
	v_cvt_pk_bf16_f32 v138, v138, v139
	v_cvt_pk_bf16_f32 v139, v136, v137
	global_store_dwordx2 v[122:123], v[138:139], off offset:512
	v_pk_mul_f32 v[136:137], v[24:25], v[124:125] op_sel_hi:[1,0]
	v_pk_mul_f32 v[138:139], v[26:27], v[124:125] op_sel_hi:[1,0]
	v_pk_fma_f32 v[136:137], v[88:89], v[136:137], v[72:73]
	v_pk_fma_f32 v[138:139], v[90:91], v[138:139], v[74:75]
	v_cvt_pk_bf16_f32 v136, v136, v137
	v_cvt_pk_bf16_f32 v137, v138, v139
	global_store_dwordx2 v[122:123], v[136:137], off offset:1024
	v_pk_mul_f32 v[136:137], v[28:29], v[124:125] op_sel_hi:[1,0]
	v_pk_mul_f32 v[124:125], v[30:31], v[124:125] op_sel_hi:[1,0]
	v_pk_fma_f32 v[136:137], v[92:93], v[136:137], v[76:77]
	v_pk_fma_f32 v[124:125], v[94:95], v[124:125], v[78:79]
	v_cvt_pk_bf16_f32 v136, v136, v137
	v_cvt_pk_bf16_f32 v137, v124, v125
	global_store_dwordx2 v[122:123], v[136:137], off offset:1536

.LBB0_250:
	s_or_b64 exec, exec, s[26:27]
	s_waitcnt vmcnt(20)
	v_mov_b32_e32 v136, v37
	v_mov_b32_e32 v137, v33
	v_mov_b32_e32 v124, v36
	v_mov_b32_e32 v125, v32
	v_pk_mul_f32 v[136:137], v[136:137], v[136:137]
	v_mov_b32_e32 v138, v45
	v_pk_fma_f32 v[124:125], v[124:125], v[124:125], v[136:137]
	v_mov_b32_e32 v136, v38
	v_mov_b32_e32 v137, v34
	v_pk_fma_f32 v[124:125], v[136:137], v[136:137], v[124:125]
	v_mov_b32_e32 v136, v39
	v_mov_b32_e32 v137, v35
	v_mov_b32_e32 v139, v41
	v_pk_fma_f32 v[124:125], v[136:137], v[136:137], v[124:125]
	v_mov_b32_e32 v136, v44
	v_mov_b32_e32 v137, v40
	v_pk_mul_f32 v[138:139], v[138:139], v[138:139]
	v_add_f32_e32 v119, v124, v125
	v_pk_fma_f32 v[136:137], v[136:137], v[136:137], v[138:139]
	v_mov_b32_e32 v138, v46
	v_mov_b32_e32 v139, v42
	v_pk_fma_f32 v[136:137], v[138:139], v[138:139], v[136:137]
	v_mov_b32_e32 v138, v47
	v_mov_b32_e32 v139, v43
	v_pk_fma_f32 v[136:137], v[138:139], v[138:139], v[136:137]
	s_nop 0
	v_add_f32_e32 v119, v137, v119
	v_add_f32_e32 v119, v136, v119
	ds_bpermute_b32 v123, v105, v119
	s_waitcnt lgkmcnt(0)
	v_add_f32_e32 v119, v119, v123
	ds_bpermute_b32 v123, v126, v119
	s_waitcnt lgkmcnt(0)
	v_add_f32_e32 v119, v119, v123
	ds_bpermute_b32 v123, v127, v119
	s_waitcnt lgkmcnt(0)
	v_add_f32_e32 v119, v119, v123
	ds_bpermute_b32 v123, v128, v119
	s_waitcnt lgkmcnt(0)
	v_add_f32_e32 v119, v119, v123
	ds_bpermute_b32 v123, v129, v119
	s_waitcnt lgkmcnt(0)
	v_add_f32_e32 v119, v119, v123
	ds_bpermute_b32 v123, v130, v119
	s_waitcnt lgkmcnt(0)
	v_add_f32_e32 v119, v119, v123
	v_fmamk_f32 v119, v119, 0x3a800000, v131
	v_mul_f32_e32 v123, 0x4b800000, v119
	v_cmp_gt_f32_e64 s[0:1], s42, v119
	s_nop 1
	v_cndmask_b32_e64 v119, v119, v123, s[0:1]
	v_rsq_f32_e32 v119, v119
	v_ashrrev_i32_e32 v123, 31, v122
	v_lshlrev_b64 v[122:123], 11, v[122:123]
	v_lshl_add_u64 v[122:123], v[100:101], 0, v[122:123]
	v_mul_f32_e32 v124, 0x45800000, v119
	v_cndmask_b32_e64 v124, v119, v124, s[0:1]
	v_pk_mul_f32 v[136:137], v[32:33], v[124:125] op_sel_hi:[1,0]
	v_pk_mul_f32 v[138:139], v[34:35], v[124:125] op_sel_hi:[1,0]
	v_pk_fma_f32 v[136:137], v[80:81], v[136:137], v[64:65]
	v_pk_fma_f32 v[138:139], v[82:83], v[138:139], v[66:67]
	v_cvt_pk_bf16_f32 v136, v136, v137
	v_cvt_pk_bf16_f32 v137, v138, v139
	v_pk_mul_f32 v[140:141], v[36:37], v[124:125] op_sel_hi:[1,0]
	global_store_dwordx2 v[122:123], v[136:137], off
	v_pk_mul_f32 v[136:137], v[38:39], v[124:125] op_sel_hi:[1,0]
	v_pk_fma_f32 v[138:139], v[84:85], v[140:141], v[68:69]
	v_pk_fma_f32 v[136:137], v[86:87], v[136:137], v[70:71]
	v_cvt_pk_bf16_f32 v138, v138, v139
	v_cvt_pk_bf16_f32 v139, v136, v137
	global_store_dwordx2 v[122:123], v[138:139], off offset:512
	v_pk_mul_f32 v[136:137], v[40:41], v[124:125] op_sel_hi:[1,0]
	v_pk_mul_f32 v[138:139], v[42:43], v[124:125] op_sel_hi:[1,0]
	v_pk_fma_f32 v[136:137], v[88:89], v[136:137], v[72:73]
	v_pk_fma_f32 v[138:139], v[90:91], v[138:139], v[74:75]
	v_cvt_pk_bf16_f32 v136, v136, v137
	v_cvt_pk_bf16_f32 v137, v138, v139
	global_store_dwordx2 v[122:123], v[136:137], off offset:1024
	v_pk_mul_f32 v[136:137], v[44:45], v[124:125] op_sel_hi:[1,0]
	v_pk_mul_f32 v[124:125], v[46:47], v[124:125] op_sel_hi:[1,0]
	v_pk_fma_f32 v[136:137], v[92:93], v[136:137], v[76:77]
	v_pk_fma_f32 v[124:125], v[94:95], v[124:125], v[78:79]
	v_cvt_pk_bf16_f32 v136, v136, v137
	v_cvt_pk_bf16_f32 v137, v124, v125
	global_store_dwordx2 v[122:123], v[136:137], off offset:1536

.LBB0_254:
	s_or_b64 exec, exec, s[24:25]
	v_ashrrev_i32_e32 v119, 12, v134
	v_cmp_ne_u32_e32 vcc, v119, v132
	s_and_saveexec_b64 s[24:25], vcc
	s_cbranch_execz .LBB0_233
	v_mul_hi_i32_i24_e32 v65, 0x6000, v119
	v_mul_i32_i24_e32 v64, 0x6000, v119
	v_lshl_add_u64 v[64:65], s[88:89], 0, v[64:65]
	v_lshl_add_u64 v[66:67], v[64:65], 0, s[14:15]
	v_lshl_add_u64 v[68:69], v[66:67], 0, v[96:97]
	global_load_dwordx4 v[80:83], v[68:69], off nt
	v_lshlrev_b32_e32 v68, 2, v102
	v_mov_b32_e32 v69, v97
	v_lshl_add_u64 v[68:69], v[66:67], 0, v[68:69]
	global_load_dwordx4 v[84:87], v[68:69], off nt
	v_lshlrev_b32_e32 v68, 2, v98
	v_mov_b32_e32 v69, v97
	v_lshl_add_u64 v[68:69], v[66:67], 0, v[68:69]
	global_load_dwordx4 v[88:91], v[68:69], off nt
	v_lshlrev_b32_e32 v68, 2, v104
	v_mov_b32_e32 v69, v97
	v_lshl_add_u64 v[66:67], v[66:67], 0, v[68:69]
	global_load_dwordx4 v[92:95], v[66:67], off nt
	global_load_dwordx4 v[122:125], v[106:107], off nt
	global_load_dwordx4 v[134:137], v[106:107], off offset:1024 nt
	v_lshl_add_u64 v[76:77], v[64:65], 0, v[96:97]
	global_load_dwordx4 v[138:141], v[106:107], off offset:2048 nt
	global_load_dwordx4 v[64:67], v[76:77], off nt
	global_load_dwordx4 v[142:145], v[106:107], off offset:3072 nt
	global_load_dwordx4 v[68:71], v[76:77], off offset:1024 nt
	global_load_dwordx4 v[72:75], v[76:77], off offset:2048 nt
	s_nop 0
	global_load_dwordx4 v[76:79], v[76:77], off offset:3072 nt
	v_mov_b32_e32 v132, v119
	s_waitcnt vmcnt(11)
	v_pk_add_f32 v[82:83], v[82:83], 1.0 op_sel_hi:[1,0]
	v_pk_add_f32 v[80:81], v[80:81], 1.0 op_sel_hi:[1,0]
	s_waitcnt vmcnt(10)
	v_pk_add_f32 v[86:87], v[86:87], 1.0 op_sel_hi:[1,0]
	v_pk_add_f32 v[84:85], v[84:85], 1.0 op_sel_hi:[1,0]
	s_waitcnt vmcnt(9)
	v_pk_add_f32 v[90:91], v[90:91], 1.0 op_sel_hi:[1,0]
	v_pk_add_f32 v[88:89], v[88:89], 1.0 op_sel_hi:[1,0]
	s_waitcnt vmcnt(8)
	v_pk_add_f32 v[94:95], v[94:95], 1.0 op_sel_hi:[1,0]
	v_pk_add_f32 v[92:93], v[92:93], 1.0 op_sel_hi:[1,0]
	s_waitcnt vmcnt(7)
	v_pk_mul_f32 v[82:83], v[124:125], v[82:83]
	v_pk_mul_f32 v[80:81], v[122:123], v[80:81]
	s_waitcnt vmcnt(6)
	v_pk_mul_f32 v[86:87], v[136:137], v[86:87]
	v_pk_mul_f32 v[84:85], v[134:135], v[84:85]
	s_waitcnt vmcnt(5)
	v_pk_mul_f32 v[90:91], v[140:141], v[90:91]
	v_pk_mul_f32 v[88:89], v[138:139], v[88:89]
	s_waitcnt vmcnt(3)
	v_pk_mul_f32 v[94:95], v[144:145], v[94:95]
	v_pk_mul_f32 v[92:93], v[142:143], v[92:93]
	s_waitcnt vmcnt(0)
	s_branch .LBB0_233
.Lnr1_t1:
	s_waitcnt vmcnt(0)
	s_branch .LBB0_237

.LBB0_1158:
	s_or_b64 exec, exec, s[4:5]
	s_waitcnt vmcnt(36)
	v_lshlrev_b32_e32 v158, 16, v153
	v_and_b32_e32 v159, 0xffff0000, v153
	v_lshlrev_b32_e32 v156, 16, v152
	v_and_b32_e32 v157, 0xffff0000, v152
	v_pk_add_f32 v[50:51], v[50:51], v[158:159]
	v_lshlrev_b32_e32 v158, 16, v151
	v_and_b32_e32 v159, 0xffff0000, v151
	v_pk_add_f32 v[48:49], v[48:49], v[156:157]
	v_lshlrev_b32_e32 v156, 16, v150
	v_and_b32_e32 v157, 0xffff0000, v150
	v_pk_add_f32 v[58:59], v[58:59], v[158:159]
	v_lshlrev_b32_e32 v158, 16, v149
	v_and_b32_e32 v159, 0xffff0000, v149
	v_pk_add_f32 v[56:57], v[56:57], v[156:157]
	v_lshlrev_b32_e32 v156, 16, v148
	v_and_b32_e32 v157, 0xffff0000, v148
	v_pk_add_f32 v[54:55], v[54:55], v[158:159]
	v_lshlrev_b32_e32 v158, 16, v147
	v_and_b32_e32 v159, 0xffff0000, v147
	v_pk_add_f32 v[52:53], v[52:53], v[156:157]
	v_lshlrev_b32_e32 v156, 16, v146
	v_and_b32_e32 v157, 0xffff0000, v146
	v_pk_add_f32 v[62:63], v[62:63], v[158:159]
	v_mov_b32_e32 v158, v57
	v_mov_b32_e32 v159, v49
	v_pk_add_f32 v[60:61], v[60:61], v[156:157]
	v_mov_b32_e32 v156, v56
	v_mov_b32_e32 v157, v48
	v_pk_mul_f32 v[158:159], v[158:159], v[158:159]
	v_mov_b32_e32 v170, v61
	v_pk_fma_f32 v[156:157], v[156:157], v[156:157], v[158:159]
	v_mov_b32_e32 v158, v58
	v_mov_b32_e32 v159, v50
	v_pk_fma_f32 v[156:157], v[158:159], v[158:159], v[156:157]
	v_mov_b32_e32 v158, v59
	v_mov_b32_e32 v159, v51
	v_mov_b32_e32 v171, v53
	v_pk_fma_f32 v[156:157], v[158:159], v[158:159], v[156:157]
	v_mov_b32_e32 v158, v60
	v_mov_b32_e32 v159, v52
	v_pk_mul_f32 v[170:171], v[170:171], v[170:171]
	v_add_f32_e32 v141, v156, v157
	v_pk_fma_f32 v[158:159], v[158:159], v[158:159], v[170:171]
	v_mov_b32_e32 v170, v62
	v_mov_b32_e32 v171, v54
	v_pk_fma_f32 v[158:159], v[170:171], v[170:171], v[158:159]
	v_mov_b32_e32 v170, v63
	v_mov_b32_e32 v171, v55
	v_pk_fma_f32 v[158:159], v[170:171], v[170:171], v[158:159]
	v_lshlrev_b64 v[154:155], 11, v[154:155]
	v_add_f32_e32 v141, v159, v141
	v_add_f32_e32 v141, v158, v141
	ds_bpermute_b32 v156, v125, v141
	v_lshl_add_u64 v[154:155], v[128:129], 0, v[154:155]
	s_waitcnt lgkmcnt(0)
	v_add_f32_e32 v141, v141, v156
	ds_bpermute_b32 v156, v127, v141
	s_waitcnt lgkmcnt(0)
	v_add_f32_e32 v141, v141, v156
	ds_bpermute_b32 v156, v162, v141
	s_waitcnt lgkmcnt(0)
	v_add_f32_e32 v141, v141, v156
	ds_bpermute_b32 v156, v163, v141
	s_waitcnt lgkmcnt(0)
	v_add_f32_e32 v141, v141, v156
	ds_bpermute_b32 v156, v164, v141
	s_waitcnt lgkmcnt(0)
	v_add_f32_e32 v141, v141, v156
	ds_bpermute_b32 v156, v165, v141
	s_waitcnt lgkmcnt(0)
	v_add_f32_e32 v141, v141, v156
	v_fmamk_f32 v141, v141, 0x3a800000, v166
	v_mul_f32_e32 v156, 0x4b800000, v141
	v_cmp_gt_f32_e32 vcc, s26, v141
	s_nop 1
	v_cndmask_b32_e32 v141, v141, v156, vcc
	v_rsq_f32_e32 v141, v141
	s_nop 0
	v_mul_f32_e32 v156, 0x45800000, v141
	v_cndmask_b32_e32 v156, v141, v156, vcc
	v_pk_mul_f32 v[158:159], v[48:49], v[156:157] op_sel_hi:[1,0]
	v_pk_mul_f32 v[170:171], v[50:51], v[156:157] op_sel_hi:[1,0]
	v_pk_fma_f32 v[158:159], v[80:81], v[158:159], v[64:65]
	v_pk_fma_f32 v[170:171], v[82:83], v[170:171], v[66:67]
	v_cvt_pk_bf16_f32 v158, v158, v159
	v_cvt_pk_bf16_f32 v159, v170, v171
	global_store_dwordx2 v[154:155], v[158:159], off
	v_pk_mul_f32 v[158:159], v[56:57], v[156:157] op_sel_hi:[1,0]
	v_pk_mul_f32 v[170:171], v[58:59], v[156:157] op_sel_hi:[1,0]
	v_pk_fma_f32 v[158:159], v[84:85], v[158:159], v[68:69]
	v_pk_fma_f32 v[170:171], v[86:87], v[170:171], v[70:71]
	v_cvt_pk_bf16_f32 v158, v158, v159
	v_cvt_pk_bf16_f32 v159, v170, v171
	global_store_dwordx2 v[154:155], v[158:159], off offset:512
	v_pk_mul_f32 v[158:159], v[52:53], v[156:157] op_sel_hi:[1,0]
	v_pk_mul_f32 v[170:171], v[54:55], v[156:157] op_sel_hi:[1,0]
	v_pk_fma_f32 v[158:159], v[88:89], v[158:159], v[72:73]
	v_pk_fma_f32 v[170:171], v[90:91], v[170:171], v[74:75]
	v_cvt_pk_bf16_f32 v158, v158, v159
	v_cvt_pk_bf16_f32 v159, v170, v171
	global_store_dwordx2 v[154:155], v[158:159], off offset:1024
	v_pk_mul_f32 v[158:159], v[60:61], v[156:157] op_sel_hi:[1,0]
	v_pk_mul_f32 v[156:157], v[62:63], v[156:157] op_sel_hi:[1,0]
	v_pk_fma_f32 v[158:159], v[92:93], v[158:159], v[76:77]
	v_pk_fma_f32 v[156:157], v[94:95], v[156:157], v[78:79]
	v_cvt_pk_bf16_f32 v158, v158, v159
	v_cvt_pk_bf16_f32 v159, v156, v157
	global_store_dwordx2 v[154:155], v[158:159], off offset:1536

.LBB0_1162:
	s_or_b64 exec, exec, s[16:17]
	v_add_u32_e32 v141, -6, v140
	v_ashrrev_i32_e32 v141, 12, v141
	v_cmp_ne_u32_e32 vcc, v141, v167
	s_and_saveexec_b64 s[16:17], vcc
	s_cbranch_execz .LBB0_1164
	v_mul_hi_i32_i24_e32 v65, 0x6000, v141
	v_mul_i32_i24_e32 v64, 0x6000, v141
	v_lshl_add_u64 v[64:65], s[88:89], 0, v[64:65]
	v_lshl_add_u64 v[66:67], v[64:65], 0, s[10:11]
	v_lshlrev_b32_e32 v68, 2, v122
	v_mov_b32_e32 v69, v97
	v_lshl_add_u64 v[76:77], v[64:65], 0, s[12:13]
	v_lshl_add_u64 v[64:65], v[66:67], 0, v[96:97]
	v_lshl_add_u64 v[70:71], v[66:67], 0, v[68:69]
	v_lshlrev_b32_e32 v72, 2, v124
	v_mov_b32_e32 v73, v97
	global_load_dwordx4 v[80:83], v[64:65], off nt
	global_load_dwordx4 v[84:87], v[70:71], off nt
	v_lshl_add_u64 v[70:71], v[66:67], 0, v[72:73]
	v_lshlrev_b32_e32 v78, 2, v126
	v_mov_b32_e32 v79, v97
	v_lshl_add_u64 v[64:65], v[76:77], 0, v[96:97]
	global_load_dwordx4 v[88:91], v[70:71], off nt
	v_lshl_add_u64 v[66:67], v[66:67], 0, v[78:79]
	v_lshl_add_u64 v[68:69], v[76:77], 0, v[68:69]
	global_load_dwordx4 v[92:95], v[66:67], off nt
	s_nop 0
	global_load_dwordx4 v[64:67], v[64:65], off nt
	s_nop 0
	global_load_dwordx4 v[156:159], v[130:131], off nt
	global_load_dwordx4 v[168:171], v[130:131], off offset:1024 nt
	s_nop 0
	global_load_dwordx4 v[68:71], v[68:69], off nt
	s_nop 0
	global_load_dwordx4 v[172:175], v[130:131], off offset:2048 nt
	v_lshl_add_u64 v[72:73], v[76:77], 0, v[72:73]
	v_lshl_add_u64 v[76:77], v[76:77], 0, v[78:79]
	global_load_dwordx4 v[176:179], v[130:131], off offset:3072 nt
	s_nop 0
	global_load_dwordx4 v[72:75], v[72:73], off nt
	v_mov_b32_e32 v167, v141
	global_load_dwordx4 v[76:79], v[76:77], off nt
	s_waitcnt vmcnt(0)
	v_pk_add_f32 v[82:83], v[82:83], 1.0 op_sel_hi:[1,0]
	v_pk_add_f32 v[80:81], v[80:81], 1.0 op_sel_hi:[1,0]
	v_pk_add_f32 v[86:87], v[86:87], 1.0 op_sel_hi:[1,0]
	v_pk_add_f32 v[84:85], v[84:85], 1.0 op_sel_hi:[1,0]
	v_pk_add_f32 v[90:91], v[90:91], 1.0 op_sel_hi:[1,0]
	v_pk_add_f32 v[88:89], v[88:89], 1.0 op_sel_hi:[1,0]
	v_pk_add_f32 v[94:95], v[94:95], 1.0 op_sel_hi:[1,0]
	v_pk_add_f32 v[92:93], v[92:93], 1.0 op_sel_hi:[1,0]
	v_pk_mul_f32 v[82:83], v[158:159], v[82:83]
	v_pk_mul_f32 v[80:81], v[156:157], v[80:81]
	v_pk_mul_f32 v[86:87], v[170:171], v[86:87]
	v_pk_mul_f32 v[84:85], v[168:169], v[84:85]
	v_pk_mul_f32 v[90:91], v[174:175], v[90:91]
	v_pk_mul_f32 v[88:89], v[172:173], v[88:89]
	v_pk_mul_f32 v[94:95], v[178:179], v[94:95]
	v_pk_mul_f32 v[92:93], v[176:177], v[92:93]
	s_waitcnt vmcnt(0)
.LBB0_1164:
	s_or_b64 exec, exec, s[16:17]
	s_waitcnt vmcnt(24)
	v_lshlrev_b32_e32 v158, 16, v99
	v_and_b32_e32 v159, 0xffff0000, v99
	v_lshlrev_b32_e32 v156, 16, v98
	v_and_b32_e32 v157, 0xffff0000, v98
	v_pk_add_f32 v[2:3], v[2:3], v[158:159]
	v_lshlrev_b32_e32 v158, 16, v101
	v_and_b32_e32 v159, 0xffff0000, v101
	v_pk_add_f32 v[0:1], v[0:1], v[156:157]
	v_lshlrev_b32_e32 v156, 16, v100
	v_and_b32_e32 v157, 0xffff0000, v100
	v_pk_add_f32 v[6:7], v[6:7], v[158:159]
	v_lshlrev_b32_e32 v158, 16, v103
	v_and_b32_e32 v159, 0xffff0000, v103
	v_pk_add_f32 v[4:5], v[4:5], v[156:157]
	v_lshlrev_b32_e32 v156, 16, v102
	v_and_b32_e32 v157, 0xffff0000, v102
	v_pk_add_f32 v[10:11], v[10:11], v[158:159]
	v_lshlrev_b32_e32 v158, 16, v105
	v_and_b32_e32 v159, 0xffff0000, v105
	v_pk_add_f32 v[8:9], v[8:9], v[156:157]
	v_lshlrev_b32_e32 v156, 16, v104
	v_and_b32_e32 v157, 0xffff0000, v104
	v_pk_add_f32 v[14:15], v[14:15], v[158:159]
	v_mov_b32_e32 v158, v5
	v_mov_b32_e32 v159, v1
	v_pk_add_f32 v[12:13], v[12:13], v[156:157]
	v_mov_b32_e32 v156, v4
	v_mov_b32_e32 v157, v0
	v_pk_mul_f32 v[158:159], v[158:159], v[158:159]
	v_mov_b32_e32 v168, v13
	v_pk_fma_f32 v[156:157], v[156:157], v[156:157], v[158:159]
	v_mov_b32_e32 v158, v6
	v_mov_b32_e32 v159, v2
	v_pk_fma_f32 v[156:157], v[158:159], v[158:159], v[156:157]
	v_mov_b32_e32 v158, v7
	v_mov_b32_e32 v159, v3
	v_mov_b32_e32 v169, v9
	v_pk_fma_f32 v[156:157], v[158:159], v[158:159], v[156:157]
	v_mov_b32_e32 v158, v12
	v_mov_b32_e32 v159, v8
	v_pk_mul_f32 v[168:169], v[168:169], v[168:169]
	v_add_f32_e32 v141, v156, v157
	v_pk_fma_f32 v[158:159], v[158:159], v[158:159], v[168:169]
	v_mov_b32_e32 v168, v14
	v_mov_b32_e32 v169, v10
	v_pk_fma_f32 v[158:159], v[168:169], v[168:169], v[158:159]
	v_mov_b32_e32 v168, v15
	v_mov_b32_e32 v169, v11
	v_pk_fma_f32 v[158:159], v[168:169], v[168:169], v[158:159]
	s_nop 0
	v_add_f32_e32 v141, v159, v141
	v_add_f32_e32 v141, v158, v141
	ds_bpermute_b32 v156, v125, v141
	v_lshl_add_u64 v[158:159], v[144:145], 0, v[136:137]
	s_waitcnt lgkmcnt(0)
	v_add_f32_e32 v141, v141, v156
	ds_bpermute_b32 v156, v127, v141
	s_waitcnt lgkmcnt(0)
	v_add_f32_e32 v141, v141, v156
	ds_bpermute_b32 v156, v162, v141
	s_waitcnt lgkmcnt(0)
	v_add_f32_e32 v141, v141, v156
	ds_bpermute_b32 v156, v163, v141
	s_waitcnt lgkmcnt(0)
	v_add_f32_e32 v141, v141, v156
	ds_bpermute_b32 v156, v164, v141
	s_waitcnt lgkmcnt(0)
	v_add_f32_e32 v141, v141, v156
	ds_bpermute_b32 v156, v165, v141
	s_waitcnt lgkmcnt(0)
	v_add_f32_e32 v141, v141, v156
	v_fmamk_f32 v141, v141, 0x3a800000, v166
	v_mul_f32_e32 v156, 0x4b800000, v141
	v_cmp_gt_f32_e32 vcc, s26, v141
	s_nop 1
	v_cndmask_b32_e32 v141, v141, v156, vcc
	v_rsq_f32_e32 v141, v141
	s_nop 0
	v_mul_f32_e32 v156, 0x45800000, v141
	v_cndmask_b32_e32 v156, v141, v156, vcc
	v_pk_mul_f32 v[168:169], v[0:1], v[156:157] op_sel_hi:[1,0]
	v_pk_mul_f32 v[170:171], v[2:3], v[156:157] op_sel_hi:[1,0]
	v_pk_fma_f32 v[168:169], v[80:81], v[168:169], v[64:65]
	v_pk_fma_f32 v[170:171], v[82:83], v[170:171], v[66:67]
	v_add_co_u32_e32 v158, vcc, s27, v158
	v_cvt_pk_bf16_f32 v168, v168, v169
	v_cvt_pk_bf16_f32 v169, v170, v171
	v_addc_co_u32_e32 v159, vcc, 0, v159, vcc
	global_store_dwordx2 v[158:159], v[168:169], off
	v_pk_mul_f32 v[168:169], v[4:5], v[156:157] op_sel_hi:[1,0]
	v_pk_mul_f32 v[170:171], v[6:7], v[156:157] op_sel_hi:[1,0]
	v_pk_fma_f32 v[168:169], v[84:85], v[168:169], v[68:69]
	v_pk_fma_f32 v[170:171], v[86:87], v[170:171], v[70:71]
	v_cvt_pk_bf16_f32 v168, v168, v169
	v_cvt_pk_bf16_f32 v169, v170, v171
	global_store_dwordx2 v[158:159], v[168:169], off offset:512
	v_pk_mul_f32 v[168:169], v[8:9], v[156:157] op_sel_hi:[1,0]
	v_pk_mul_f32 v[170:171], v[10:11], v[156:157] op_sel_hi:[1,0]
	v_pk_fma_f32 v[168:169], v[88:89], v[168:169], v[72:73]
	v_pk_fma_f32 v[170:171], v[90:91], v[170:171], v[74:75]
	v_cvt_pk_bf16_f32 v168, v168, v169
	v_cvt_pk_bf16_f32 v169, v170, v171
	global_store_dwordx2 v[158:159], v[168:169], off offset:1024
	v_pk_mul_f32 v[168:169], v[12:13], v[156:157] op_sel_hi:[1,0]
	v_pk_mul_f32 v[156:157], v[14:15], v[156:157] op_sel_hi:[1,0]
	v_pk_fma_f32 v[168:169], v[92:93], v[168:169], v[76:77]
	v_pk_fma_f32 v[156:157], v[94:95], v[156:157], v[78:79]
	v_cvt_pk_bf16_f32 v168, v168, v169
	v_cvt_pk_bf16_f32 v169, v156, v157
	v_add_u32_e32 v156, -5, v140
	global_store_dwordx2 v[158:159], v[168:169], off offset:1536
	v_cmp_lt_i32_e32 vcc, v156, v123
	v_add_u32_e32 v168, -2, v140
	s_and_saveexec_b64 s[16:17], vcc
	s_cbranch_execz .LBB0_1170
	v_cmp_lt_i32_e32 vcc, v168, v123
	s_and_saveexec_b64 s[24:25], vcc
	s_cbranch_execz .Lnr9_t2
	v_lshl_add_u64 v[0:1], v[138:139], 0, v[136:137]
	v_add_co_u32_e32 v104, vcc, 0x154bc000, v0
	s_nop 1
	v_addc_co_u32_e32 v105, vcc, 0, v1, vcc
	global_load_dwordx4 v[0:3], v[142:143], off offset:-3072 nt
	global_load_dwordx4 v[4:7], v[142:143], off offset:-2048 nt
	global_load_dwordx4 v[8:11], v[142:143], off offset:-1024 nt
	global_load_dwordx4 v[12:15], v[142:143], off nt
	global_load_dwordx2 v[98:99], v[104:105], off
	global_load_dwordx2 v[100:101], v[104:105], off offset:512
	global_load_dwordx2 v[102:103], v[104:105], off offset:1024
	s_nop 0
	global_load_dwordx2 v[104:105], v[104:105], off offset:1536
.LBB0_1167:
	s_or_b64 exec, exec, s[24:25]
	v_ashrrev_i32_e32 v141, 12, v156
	v_cmp_ne_u32_e32 vcc, v141, v167
	s_and_saveexec_b64 s[24:25], vcc
	s_cbranch_execz .LBB0_1169
	v_mul_hi_i32_i24_e32 v65, 0x6000, v141
	v_mul_i32_i24_e32 v64, 0x6000, v141
	v_lshl_add_u64 v[64:65], s[88:89], 0, v[64:65]
	v_lshl_add_u64 v[66:67], v[64:65], 0, s[10:11]
	v_lshlrev_b32_e32 v68, 2, v122
	v_mov_b32_e32 v69, v97
	v_lshl_add_u64 v[76:77], v[64:65], 0, s[12:13]
	v_lshl_add_u64 v[64:65], v[66:67], 0, v[96:97]
	v_lshl_add_u64 v[70:71], v[66:67], 0, v[68:69]
	v_lshlrev_b32_e32 v72, 2, v124
	v_mov_b32_e32 v73, v97
	global_load_dwordx4 v[80:83], v[64:65], off nt
	global_load_dwordx4 v[84:87], v[70:71], off nt
	v_lshl_add_u64 v[70:71], v[66:67], 0, v[72:73]
	v_lshlrev_b32_e32 v78, 2, v126
	v_mov_b32_e32 v79, v97
	v_lshl_add_u64 v[64:65], v[76:77], 0, v[96:97]
	global_load_dwordx4 v[88:91], v[70:71], off nt
	v_lshl_add_u64 v[66:67], v[66:67], 0, v[78:79]
	v_lshl_add_u64 v[68:69], v[76:77], 0, v[68:69]
	global_load_dwordx4 v[92:95], v[66:67], off nt
	s_nop 0
	global_load_dwordx4 v[64:67], v[64:65], off nt
	s_nop 0
	global_load_dwordx4 v[170:173], v[130:131], off nt
	global_load_dwordx4 v[174:177], v[130:131], off offset:1024 nt
	s_nop 0
	global_load_dwordx4 v[68:71], v[68:69], off nt
	s_nop 0
	global_load_dwordx4 v[178:181], v[130:131], off offset:2048 nt
	v_lshl_add_u64 v[72:73], v[76:77], 0, v[72:73]
	v_lshl_add_u64 v[76:77], v[76:77], 0, v[78:79]
	global_load_dwordx4 v[182:185], v[130:131], off offset:3072 nt
	s_nop 0
	global_load_dwordx4 v[72:75], v[72:73], off nt
	v_mov_b32_e32 v167, v141
	global_load_dwordx4 v[76:79], v[76:77], off nt
	s_waitcnt vmcnt(11)
	v_pk_add_f32 v[82:83], v[82:83], 1.0 op_sel_hi:[1,0]
	v_pk_add_f32 v[80:81], v[80:81], 1.0 op_sel_hi:[1,0]
	s_waitcnt vmcnt(10)
	v_pk_add_f32 v[86:87], v[86:87], 1.0 op_sel_hi:[1,0]
	v_pk_add_f32 v[84:85], v[84:85], 1.0 op_sel_hi:[1,0]
	s_waitcnt vmcnt(9)
	v_pk_add_f32 v[90:91], v[90:91], 1.0 op_sel_hi:[1,0]
	v_pk_add_f32 v[88:89], v[88:89], 1.0 op_sel_hi:[1,0]
	s_waitcnt vmcnt(8)
	v_pk_add_f32 v[94:95], v[94:95], 1.0 op_sel_hi:[1,0]
	v_pk_add_f32 v[92:93], v[92:93], 1.0 op_sel_hi:[1,0]
	s_waitcnt vmcnt(6)
	v_pk_mul_f32 v[82:83], v[172:173], v[82:83]
	v_pk_mul_f32 v[80:81], v[170:171], v[80:81]
	s_waitcnt vmcnt(5)
	v_pk_mul_f32 v[86:87], v[176:177], v[86:87]
	v_pk_mul_f32 v[84:85], v[174:175], v[84:85]
	s_waitcnt vmcnt(3)
	v_pk_mul_f32 v[90:91], v[180:181], v[90:91]
	v_pk_mul_f32 v[88:89], v[178:179], v[88:89]
	s_waitcnt vmcnt(2)
	v_pk_mul_f32 v[94:95], v[184:185], v[94:95]
	v_pk_mul_f32 v[92:93], v[182:183], v[92:93]
	s_waitcnt vmcnt(0)
.LBB0_1169:
	s_or_b64 exec, exec, s[24:25]
	s_waitcnt vmcnt(28)
	v_lshlrev_b32_e32 v170, 16, v107
	v_and_b32_e32 v171, 0xffff0000, v107
	v_lshlrev_b32_e32 v158, 16, v106
	v_and_b32_e32 v159, 0xffff0000, v106
	v_pk_add_f32 v[18:19], v[18:19], v[170:171]
	v_lshlrev_b32_e32 v170, 16, v109
	v_and_b32_e32 v171, 0xffff0000, v109
	v_pk_add_f32 v[16:17], v[16:17], v[158:159]
	v_lshlrev_b32_e32 v158, 16, v108
	v_and_b32_e32 v159, 0xffff0000, v108
	v_pk_add_f32 v[22:23], v[22:23], v[170:171]
	v_lshlrev_b32_e32 v170, 16, v111
	v_and_b32_e32 v171, 0xffff0000, v111
	v_pk_add_f32 v[20:21], v[20:21], v[158:159]
	v_lshlrev_b32_e32 v158, 16, v110
	v_and_b32_e32 v159, 0xffff0000, v110
	v_pk_add_f32 v[26:27], v[26:27], v[170:171]
	v_lshlrev_b32_e32 v170, 16, v113
	v_and_b32_e32 v171, 0xffff0000, v113
	v_pk_add_f32 v[24:25], v[24:25], v[158:159]
	v_lshlrev_b32_e32 v158, 16, v112
	v_and_b32_e32 v159, 0xffff0000, v112
	v_pk_add_f32 v[30:31], v[30:31], v[170:171]
	v_mov_b32_e32 v170, v21
	v_mov_b32_e32 v171, v17
	v_pk_add_f32 v[28:29], v[28:29], v[158:159]
	v_mov_b32_e32 v158, v20
	v_mov_b32_e32 v159, v16
	v_pk_mul_f32 v[170:171], v[170:171], v[170:171]
	v_mov_b32_e32 v172, v29
	v_pk_fma_f32 v[158:159], v[158:159], v[158:159], v[170:171]
	v_mov_b32_e32 v170, v22
	v_mov_b32_e32 v171, v18
	v_pk_fma_f32 v[158:159], v[170:171], v[170:171], v[158:159]
	v_mov_b32_e32 v170, v23
	v_mov_b32_e32 v171, v19
	v_mov_b32_e32 v173, v25
	v_pk_fma_f32 v[158:159], v[170:171], v[170:171], v[158:159]
	v_mov_b32_e32 v170, v28
	v_mov_b32_e32 v171, v24
	v_pk_mul_f32 v[172:173], v[172:173], v[172:173]
	v_add_f32_e32 v141, v158, v159
	v_pk_fma_f32 v[170:171], v[170:171], v[170:171], v[172:173]
	v_mov_b32_e32 v172, v30
	v_mov_b32_e32 v173, v26
	v_pk_fma_f32 v[170:171], v[172:173], v[172:173], v[170:171]
	v_mov_b32_e32 v172, v31
	v_mov_b32_e32 v173, v27
	v_pk_fma_f32 v[170:171], v[172:173], v[172:173], v[170:171]
	s_nop 0
	v_add_f32_e32 v141, v171, v141
	v_add_f32_e32 v141, v170, v141
	ds_bpermute_b32 v157, v125, v141
	s_waitcnt lgkmcnt(0)
	v_add_f32_e32 v141, v141, v157
	ds_bpermute_b32 v157, v127, v141
	s_waitcnt lgkmcnt(0)
	v_add_f32_e32 v141, v141, v157
	ds_bpermute_b32 v157, v162, v141
	s_waitcnt lgkmcnt(0)
	v_add_f32_e32 v141, v141, v157
	ds_bpermute_b32 v157, v163, v141
	s_waitcnt lgkmcnt(0)
	v_add_f32_e32 v141, v141, v157
	ds_bpermute_b32 v157, v164, v141
	s_waitcnt lgkmcnt(0)
	v_add_f32_e32 v141, v141, v157
	ds_bpermute_b32 v157, v165, v141
	s_waitcnt lgkmcnt(0)
	v_add_f32_e32 v141, v141, v157
	v_fmamk_f32 v141, v141, 0x3a800000, v166
	v_mul_f32_e32 v157, 0x4b800000, v141
	v_cmp_gt_f32_e32 vcc, s26, v141
	s_nop 1
	v_cndmask_b32_e32 v141, v141, v157, vcc
	v_rsq_f32_e32 v141, v141
	s_nop 0
	v_mul_f32_e32 v157, 0x45800000, v141
	v_cndmask_b32_e32 v158, v141, v157, vcc
	v_ashrrev_i32_e32 v157, 31, v156
	v_pk_mul_f32 v[170:171], v[16:17], v[158:159] op_sel_hi:[1,0]
	v_pk_mul_f32 v[172:173], v[18:19], v[158:159] op_sel_hi:[1,0]
	v_lshlrev_b64 v[156:157], 11, v[156:157]
	v_pk_fma_f32 v[172:173], v[82:83], v[172:173], v[66:67]
	v_pk_fma_f32 v[170:171], v[80:81], v[170:171], v[64:65]
	v_lshl_add_u64 v[156:157], v[128:129], 0, v[156:157]
	v_cvt_pk_bf16_f32 v170, v170, v171
	v_cvt_pk_bf16_f32 v171, v172, v173
	global_store_dwordx2 v[156:157], v[170:171], off
	v_pk_mul_f32 v[170:171], v[20:21], v[158:159] op_sel_hi:[1,0]
	v_pk_mul_f32 v[172:173], v[22:23], v[158:159] op_sel_hi:[1,0]
	v_pk_fma_f32 v[170:171], v[84:85], v[170:171], v[68:69]
	v_pk_fma_f32 v[172:173], v[86:87], v[172:173], v[70:71]
	v_cvt_pk_bf16_f32 v170, v170, v171
	v_cvt_pk_bf16_f32 v171, v172, v173
	global_store_dwordx2 v[156:157], v[170:171], off offset:512
	v_pk_mul_f32 v[170:171], v[24:25], v[158:159] op_sel_hi:[1,0]
	v_pk_mul_f32 v[172:173], v[26:27], v[158:159] op_sel_hi:[1,0]
	v_pk_fma_f32 v[170:171], v[88:89], v[170:171], v[72:73]
	v_pk_fma_f32 v[172:173], v[90:91], v[172:173], v[74:75]
	v_cvt_pk_bf16_f32 v170, v170, v171
	v_cvt_pk_bf16_f32 v171, v172, v173
	global_store_dwordx2 v[156:157], v[170:171], off offset:1024
	v_pk_mul_f32 v[170:171], v[28:29], v[158:159] op_sel_hi:[1,0]
	v_pk_mul_f32 v[158:159], v[30:31], v[158:159] op_sel_hi:[1,0]
	v_pk_fma_f32 v[170:171], v[92:93], v[170:171], v[76:77]
	v_pk_fma_f32 v[158:159], v[94:95], v[158:159], v[78:79]
	v_cvt_pk_bf16_f32 v170, v170, v171
	v_cvt_pk_bf16_f32 v171, v158, v159
	global_store_dwordx2 v[156:157], v[170:171], off offset:1536

.LBB0_1175:
	s_or_b64 exec, exec, s[24:25]
	s_waitcnt vmcnt(32)
	v_lshlrev_b32_e32 v170, 16, v115
	v_and_b32_e32 v171, 0xffff0000, v115
	v_lshlrev_b32_e32 v158, 16, v114
	v_and_b32_e32 v159, 0xffff0000, v114
	v_pk_add_f32 v[34:35], v[34:35], v[170:171]
	v_lshlrev_b32_e32 v170, 16, v117
	v_and_b32_e32 v171, 0xffff0000, v117
	v_pk_add_f32 v[32:33], v[32:33], v[158:159]
	v_lshlrev_b32_e32 v158, 16, v116
	v_and_b32_e32 v159, 0xffff0000, v116
	v_pk_add_f32 v[38:39], v[38:39], v[170:171]
	v_lshlrev_b32_e32 v170, 16, v119
	v_and_b32_e32 v171, 0xffff0000, v119
	v_pk_add_f32 v[36:37], v[36:37], v[158:159]
	v_lshlrev_b32_e32 v158, 16, v118
	v_and_b32_e32 v159, 0xffff0000, v118
	v_pk_add_f32 v[42:43], v[42:43], v[170:171]
	v_lshlrev_b32_e32 v170, 16, v121
	v_and_b32_e32 v171, 0xffff0000, v121
	v_pk_add_f32 v[40:41], v[40:41], v[158:159]
	v_lshlrev_b32_e32 v158, 16, v120
	v_and_b32_e32 v159, 0xffff0000, v120
	v_pk_add_f32 v[46:47], v[46:47], v[170:171]
	v_mov_b32_e32 v170, v37
	v_mov_b32_e32 v171, v33
	v_pk_add_f32 v[44:45], v[44:45], v[158:159]
	v_mov_b32_e32 v158, v36
	v_mov_b32_e32 v159, v32
	v_pk_mul_f32 v[170:171], v[170:171], v[170:171]
	v_mov_b32_e32 v172, v45
	v_pk_fma_f32 v[158:159], v[158:159], v[158:159], v[170:171]
	v_mov_b32_e32 v170, v38
	v_mov_b32_e32 v171, v34
	v_pk_fma_f32 v[158:159], v[170:171], v[170:171], v[158:159]
	v_mov_b32_e32 v170, v39
	v_mov_b32_e32 v171, v35
	v_mov_b32_e32 v173, v41
	v_pk_fma_f32 v[158:159], v[170:171], v[170:171], v[158:159]
	v_mov_b32_e32 v170, v44
	v_mov_b32_e32 v171, v40
	v_pk_mul_f32 v[172:173], v[172:173], v[172:173]
	v_add_f32_e32 v141, v158, v159
	v_pk_fma_f32 v[170:171], v[170:171], v[170:171], v[172:173]
	v_mov_b32_e32 v172, v46
	v_mov_b32_e32 v173, v42
	v_pk_fma_f32 v[170:171], v[172:173], v[172:173], v[170:171]
	v_mov_b32_e32 v172, v47
	v_mov_b32_e32 v173, v43
	v_pk_fma_f32 v[170:171], v[172:173], v[172:173], v[170:171]
	s_nop 0
	v_add_f32_e32 v141, v171, v141
	v_add_f32_e32 v141, v170, v141
	ds_bpermute_b32 v157, v125, v141
	s_waitcnt lgkmcnt(0)
	v_add_f32_e32 v141, v141, v157
	ds_bpermute_b32 v157, v127, v141
	s_waitcnt lgkmcnt(0)
	v_add_f32_e32 v141, v141, v157
	ds_bpermute_b32 v157, v162, v141
	s_waitcnt lgkmcnt(0)
	v_add_f32_e32 v141, v141, v157
	ds_bpermute_b32 v157, v163, v141
	s_waitcnt lgkmcnt(0)
	v_add_f32_e32 v141, v141, v157
	ds_bpermute_b32 v157, v164, v141
	s_waitcnt lgkmcnt(0)
	v_add_f32_e32 v141, v141, v157
	ds_bpermute_b32 v157, v165, v141
	s_waitcnt lgkmcnt(0)
	v_add_f32_e32 v141, v141, v157
	v_fmamk_f32 v141, v141, 0x3a800000, v166
	v_mul_f32_e32 v157, 0x4b800000, v141
	v_cmp_gt_f32_e32 vcc, s26, v141
	s_nop 1
	v_cndmask_b32_e32 v141, v141, v157, vcc
	v_rsq_f32_e32 v141, v141
	s_nop 0
	v_mul_f32_e32 v157, 0x45800000, v141
	v_cndmask_b32_e32 v158, v141, v157, vcc
	v_ashrrev_i32_e32 v157, 31, v156
	v_pk_mul_f32 v[170:171], v[32:33], v[158:159] op_sel_hi:[1,0]
	v_pk_mul_f32 v[172:173], v[34:35], v[158:159] op_sel_hi:[1,0]
	v_lshlrev_b64 v[156:157], 11, v[156:157]
	v_pk_fma_f32 v[172:173], v[82:83], v[172:173], v[66:67]
	v_pk_fma_f32 v[170:171], v[80:81], v[170:171], v[64:65]
	v_lshl_add_u64 v[156:157], v[128:129], 0, v[156:157]
	v_cvt_pk_bf16_f32 v170, v170, v171
	v_cvt_pk_bf16_f32 v171, v172, v173
	global_store_dwordx2 v[156:157], v[170:171], off
	v_pk_mul_f32 v[170:171], v[36:37], v[158:159] op_sel_hi:[1,0]
	v_pk_mul_f32 v[172:173], v[38:39], v[158:159] op_sel_hi:[1,0]
	v_pk_fma_f32 v[170:171], v[84:85], v[170:171], v[68:69]
	v_pk_fma_f32 v[172:173], v[86:87], v[172:173], v[70:71]
	v_cvt_pk_bf16_f32 v170, v170, v171
	v_cvt_pk_bf16_f32 v171, v172, v173
	global_store_dwordx2 v[156:157], v[170:171], off offset:512
	v_pk_mul_f32 v[170:171], v[40:41], v[158:159] op_sel_hi:[1,0]
	v_pk_mul_f32 v[172:173], v[42:43], v[158:159] op_sel_hi:[1,0]
	v_pk_fma_f32 v[170:171], v[88:89], v[170:171], v[72:73]
	v_pk_fma_f32 v[172:173], v[90:91], v[172:173], v[74:75]
	v_cvt_pk_bf16_f32 v170, v170, v171
	v_cvt_pk_bf16_f32 v171, v172, v173
	global_store_dwordx2 v[156:157], v[170:171], off offset:1024
	v_pk_mul_f32 v[170:171], v[44:45], v[158:159] op_sel_hi:[1,0]
	v_pk_mul_f32 v[158:159], v[46:47], v[158:159] op_sel_hi:[1,0]
	v_pk_fma_f32 v[170:171], v[92:93], v[170:171], v[76:77]
	v_pk_fma_f32 v[158:159], v[94:95], v[158:159], v[78:79]
	v_cvt_pk_bf16_f32 v170, v170, v171
	v_cvt_pk_bf16_f32 v171, v158, v159
	global_store_dwordx2 v[156:157], v[170:171], off offset:1536

.LBB0_1179:
	s_or_b64 exec, exec, s[4:5]
	v_ashrrev_i32_e32 v141, 12, v154
	v_cmp_ne_u32_e32 vcc, v141, v167
	s_and_saveexec_b64 s[4:5], vcc
	s_cbranch_execz .LBB0_1158
	v_mul_hi_i32_i24_e32 v65, 0x6000, v141
	v_mul_i32_i24_e32 v64, 0x6000, v141
	v_lshl_add_u64 v[64:65], s[88:89], 0, v[64:65]
	v_lshl_add_u64 v[66:67], v[64:65], 0, s[10:11]
	v_lshlrev_b32_e32 v68, 2, v122
	v_mov_b32_e32 v69, v97
	v_lshl_add_u64 v[76:77], v[64:65], 0, s[12:13]
	v_lshl_add_u64 v[64:65], v[66:67], 0, v[96:97]
	v_lshl_add_u64 v[70:71], v[66:67], 0, v[68:69]
	v_lshlrev_b32_e32 v72, 2, v124
	v_mov_b32_e32 v73, v97
	global_load_dwordx4 v[80:83], v[64:65], off nt
	global_load_dwordx4 v[84:87], v[70:71], off nt
	v_lshl_add_u64 v[70:71], v[66:67], 0, v[72:73]
	v_lshlrev_b32_e32 v78, 2, v126
	v_mov_b32_e32 v79, v97
	v_lshl_add_u64 v[64:65], v[76:77], 0, v[96:97]
	global_load_dwordx4 v[88:91], v[70:71], off nt
	v_lshl_add_u64 v[66:67], v[66:67], 0, v[78:79]
	v_lshl_add_u64 v[68:69], v[76:77], 0, v[68:69]
	global_load_dwordx4 v[92:95], v[66:67], off nt
	s_nop 0
	global_load_dwordx4 v[64:67], v[64:65], off nt
	s_nop 0
	global_load_dwordx4 v[156:159], v[130:131], off nt
	global_load_dwordx4 v[170:173], v[130:131], off offset:1024 nt
	s_nop 0
	global_load_dwordx4 v[68:71], v[68:69], off nt
	s_nop 0
	global_load_dwordx4 v[174:177], v[130:131], off offset:2048 nt
	v_lshl_add_u64 v[72:73], v[76:77], 0, v[72:73]
	v_lshl_add_u64 v[76:77], v[76:77], 0, v[78:79]
	global_load_dwordx4 v[178:181], v[130:131], off offset:3072 nt
	s_nop 0
	global_load_dwordx4 v[72:75], v[72:73], off nt
	v_mov_b32_e32 v167, v141
	global_load_dwordx4 v[76:79], v[76:77], off nt
	s_waitcnt vmcnt(11)
	v_pk_add_f32 v[82:83], v[82:83], 1.0 op_sel_hi:[1,0]
	v_pk_add_f32 v[80:81], v[80:81], 1.0 op_sel_hi:[1,0]
	s_waitcnt vmcnt(10)
	v_pk_add_f32 v[86:87], v[86:87], 1.0 op_sel_hi:[1,0]
	v_pk_add_f32 v[84:85], v[84:85], 1.0 op_sel_hi:[1,0]
	s_waitcnt vmcnt(9)
	v_pk_add_f32 v[90:91], v[90:91], 1.0 op_sel_hi:[1,0]
	v_pk_add_f32 v[88:89], v[88:89], 1.0 op_sel_hi:[1,0]
	s_waitcnt vmcnt(8)
	v_pk_add_f32 v[94:95], v[94:95], 1.0 op_sel_hi:[1,0]
	v_pk_add_f32 v[92:93], v[92:93], 1.0 op_sel_hi:[1,0]
	s_waitcnt vmcnt(6)
	v_pk_mul_f32 v[82:83], v[158:159], v[82:83]
	v_pk_mul_f32 v[80:81], v[156:157], v[80:81]
	s_waitcnt vmcnt(5)
	v_pk_mul_f32 v[86:87], v[172:173], v[86:87]
	v_pk_mul_f32 v[84:85], v[170:171], v[84:85]
	s_waitcnt vmcnt(3)
	v_pk_mul_f32 v[90:91], v[176:177], v[90:91]
	v_pk_mul_f32 v[88:89], v[174:175], v[88:89]
	s_waitcnt vmcnt(2)
	v_pk_mul_f32 v[94:95], v[180:181], v[94:95]
	v_pk_mul_f32 v[92:93], v[178:179], v[92:93]
	s_waitcnt vmcnt(0)
	s_branch .LBB0_1158
